# previous version + p to fp16 conversion loops de-serialised (8 loads in flight per lane, counted vmcnt instead of load/wait/store per iteration)
# speedup vs baseline: 1.0035x; 1.0035x over previous
; #define GB_P16(g)  ((h16*)gbuf(ws, g, OFF_P16, 512))
; __device__ __forceinline__ void convert_p(const Args& a, int layer, int g, int nb, int cb, int tid) {
;     unsigned char* ws = a.ws; const int rows = g ? MS : MP, row0 = g ? MP : 0;
;     u32x2* o = (u32x2*)(GB_P16(g) + (size_t)row0 * PLE);
;     const f32x4* p = (const f32x4*)((g ? a.in[I_PS] + (size_t)layer * MS * PLE : a.in[I_PP] + (size_t)layer * MP * PLE));
;     const int N4 = rows * PLE / 4;
;     for (int i = cb * NTHREADS + tid; i < N4; i += nb * NTHREADS) { const f32x4 v = p[i]; u32x2 w; w.x = pk2h(v.x, v.y); w.y = pk2h(v.z, v.w); o[i] = w; }
; }
.LBB0_770:
	global_load_dwordx4 v[6:9], v[2:3], off
	v_lshl_add_u64 v[2:3], v[2:3], 0, s[8:9]
	global_load_dwordx4 v[10:13], v[2:3], off
	v_lshl_add_u64 v[2:3], v[2:3], 0, s[8:9]
	global_load_dwordx4 v[14:17], v[2:3], off
	v_lshl_add_u64 v[2:3], v[2:3], 0, s[8:9]
	global_load_dwordx4 v[18:21], v[2:3], off
	v_lshl_add_u64 v[2:3], v[2:3], 0, s[8:9]
	global_load_dwordx4 v[22:25], v[2:3], off
	v_lshl_add_u64 v[2:3], v[2:3], 0, s[8:9]
	global_load_dwordx4 v[26:29], v[2:3], off
	v_lshl_add_u64 v[2:3], v[2:3], 0, s[8:9]
	global_load_dwordx4 v[30:33], v[2:3], off
	v_lshl_add_u64 v[2:3], v[2:3], 0, s[8:9]
	global_load_dwordx4 v[34:37], v[2:3], off
	v_lshl_add_u64 v[2:3], v[2:3], 0, s[8:9]
	s_lshl_b32 s7, s36, 3
	v_add_u32_e32 v0, s7, v0
	s_mov_b32 s6, 0x3fffff
	v_cmp_lt_i32_e32 vcc, s6, v0
	s_waitcnt vmcnt(7)
	v_cvt_pk_f16_f32 v6, v6, v7
	v_cvt_pk_f16_f32 v7, v8, v9
	global_store_dwordx2 v[4:5], v[6:7], off
	v_lshl_add_u64 v[4:5], v[4:5], 0, s[10:11]
	s_or_b64 s[4:5], vcc, s[4:5]
	s_waitcnt vmcnt(7)
	v_cvt_pk_f16_f32 v10, v10, v11
	v_cvt_pk_f16_f32 v11, v12, v13
	global_store_dwordx2 v[4:5], v[10:11], off
	v_lshl_add_u64 v[4:5], v[4:5], 0, s[10:11]
	s_waitcnt vmcnt(7)
	v_cvt_pk_f16_f32 v14, v14, v15
	v_cvt_pk_f16_f32 v15, v16, v17
	global_store_dwordx2 v[4:5], v[14:15], off
	v_lshl_add_u64 v[4:5], v[4:5], 0, s[10:11]
	s_waitcnt vmcnt(7)
	v_cvt_pk_f16_f32 v18, v18, v19
	v_cvt_pk_f16_f32 v19, v20, v21
	global_store_dwordx2 v[4:5], v[18:19], off
	v_lshl_add_u64 v[4:5], v[4:5], 0, s[10:11]
	s_waitcnt vmcnt(7)
	v_cvt_pk_f16_f32 v22, v22, v23
	v_cvt_pk_f16_f32 v23, v24, v25
	global_store_dwordx2 v[4:5], v[22:23], off
	v_lshl_add_u64 v[4:5], v[4:5], 0, s[10:11]
	s_waitcnt vmcnt(7)
	v_cvt_pk_f16_f32 v26, v26, v27
	v_cvt_pk_f16_f32 v27, v28, v29
	global_store_dwordx2 v[4:5], v[26:27], off
	v_lshl_add_u64 v[4:5], v[4:5], 0, s[10:11]
	s_waitcnt vmcnt(7)
	v_cvt_pk_f16_f32 v30, v30, v31
	v_cvt_pk_f16_f32 v31, v32, v33
	global_store_dwordx2 v[4:5], v[30:31], off
	v_lshl_add_u64 v[4:5], v[4:5], 0, s[10:11]
	s_waitcnt vmcnt(7)
	v_cvt_pk_f16_f32 v34, v34, v35
	v_cvt_pk_f16_f32 v35, v36, v37
	global_store_dwordx2 v[4:5], v[34:35], off
	v_lshl_add_u64 v[4:5], v[4:5], 0, s[10:11]
	s_andn2_b64 exec, exec, s[4:5]
	s_cbranch_execnz .LBB0_770

; #define GB_P16(g)  ((h16*)gbuf(ws, g, OFF_P16, 512))
; __device__ __forceinline__ void convert_p(const Args& a, int layer, int g, int nb, int cb, int tid) {
;     unsigned char* ws = a.ws; const int rows = g ? MS : MP, row0 = g ? MP : 0;
;     u32x2* o = (u32x2*)(GB_P16(g) + (size_t)row0 * PLE);
;     const f32x4* p = (const f32x4*)((g ? a.in[I_PS] + (size_t)layer * MS * PLE : a.in[I_PP] + (size_t)layer * MP * PLE));
;     const int N4 = rows * PLE / 4;
;     for (int i = cb * NTHREADS + tid; i < N4; i += nb * NTHREADS) { const f32x4 v = p[i]; u32x2 w; w.x = pk2h(v.x, v.y); w.y = pk2h(v.z, v.w); o[i] = w; }
; }
.LBB0_957:
	global_load_dwordx4 v[6:9], v[2:3], off
	v_lshl_add_u64 v[2:3], v[2:3], 0, s[8:9]
	global_load_dwordx4 v[10:13], v[2:3], off
	v_lshl_add_u64 v[2:3], v[2:3], 0, s[8:9]
	global_load_dwordx4 v[14:17], v[2:3], off
	v_lshl_add_u64 v[2:3], v[2:3], 0, s[8:9]
	global_load_dwordx4 v[18:21], v[2:3], off
	v_lshl_add_u64 v[2:3], v[2:3], 0, s[8:9]
	global_load_dwordx4 v[22:25], v[2:3], off
	v_lshl_add_u64 v[2:3], v[2:3], 0, s[8:9]
	global_load_dwordx4 v[26:29], v[2:3], off
	v_lshl_add_u64 v[2:3], v[2:3], 0, s[8:9]
	global_load_dwordx4 v[30:33], v[2:3], off
	v_lshl_add_u64 v[2:3], v[2:3], 0, s[8:9]
	global_load_dwordx4 v[34:37], v[2:3], off
	v_lshl_add_u64 v[2:3], v[2:3], 0, s[8:9]
	s_lshl_b32 s7, s36, 3
	v_add_u32_e32 v0, s7, v0
	s_mov_b32 s6, 0x1fffff
	v_cmp_lt_i32_e32 vcc, s6, v0
	s_waitcnt vmcnt(7)
	v_cvt_pk_f16_f32 v6, v6, v7
	v_cvt_pk_f16_f32 v7, v8, v9
	global_store_dwordx2 v[4:5], v[6:7], off
	v_lshl_add_u64 v[4:5], v[4:5], 0, s[10:11]
	s_or_b64 s[4:5], vcc, s[4:5]
	s_waitcnt vmcnt(7)
	v_cvt_pk_f16_f32 v10, v10, v11
	v_cvt_pk_f16_f32 v11, v12, v13
	global_store_dwordx2 v[4:5], v[10:11], off
	v_lshl_add_u64 v[4:5], v[4:5], 0, s[10:11]
	s_waitcnt vmcnt(7)
	v_cvt_pk_f16_f32 v14, v14, v15
	v_cvt_pk_f16_f32 v15, v16, v17
	global_store_dwordx2 v[4:5], v[14:15], off
	v_lshl_add_u64 v[4:5], v[4:5], 0, s[10:11]
	s_waitcnt vmcnt(7)
	v_cvt_pk_f16_f32 v18, v18, v19
	v_cvt_pk_f16_f32 v19, v20, v21
	global_store_dwordx2 v[4:5], v[18:19], off
	v_lshl_add_u64 v[4:5], v[4:5], 0, s[10:11]
	s_waitcnt vmcnt(7)
	v_cvt_pk_f16_f32 v22, v22, v23
	v_cvt_pk_f16_f32 v23, v24, v25
	global_store_dwordx2 v[4:5], v[22:23], off
	v_lshl_add_u64 v[4:5], v[4:5], 0, s[10:11]
	s_waitcnt vmcnt(7)
	v_cvt_pk_f16_f32 v26, v26, v27
	v_cvt_pk_f16_f32 v27, v28, v29
	global_store_dwordx2 v[4:5], v[26:27], off
	v_lshl_add_u64 v[4:5], v[4:5], 0, s[10:11]
	s_waitcnt vmcnt(7)
	v_cvt_pk_f16_f32 v30, v30, v31
	v_cvt_pk_f16_f32 v31, v32, v33
	global_store_dwordx2 v[4:5], v[30:31], off
	v_lshl_add_u64 v[4:5], v[4:5], 0, s[10:11]
	s_waitcnt vmcnt(7)
	v_cvt_pk_f16_f32 v34, v34, v35
	v_cvt_pk_f16_f32 v35, v36, v37
	global_store_dwordx2 v[4:5], v[34:35], off
	v_lshl_add_u64 v[4:5], v[4:5], 0, s[10:11]
	s_andn2_b64 exec, exec, s[4:5]
	s_cbranch_execnz .LBB0_957
